# attention: lazy running max (scores relative to the current row maximum come straight out of the MFMA; subtraction only on a new maximum)
# baseline (speedup 1.0000x reference)
; #define LAS __attribute__((address_space(3)))
; __device__ __forceinline__ float fexp2(float x) { return __builtin_amdgcn_exp2f(x); }
; #define PREFETCH(t) do { \
;         _Pragma("unroll") for (int i_ = 0; i_ < 4; ++i_) { const int pid_ = tid + 512 * i_, row_ = pid_ >> 4, c16_ = pid_ & 15; const unsigned go_ = (tokb + (unsigned)((t) * 128 + row_)) * 2048u + (unsigned)(hd * 128 + 8 * c16_); \
;             preK[i_] = *(const u32x4*)(Kb + go_); preV[i_] = *(const u32x4*)(Vb + go_); } \
;     } while (0)
; #define STAGE_WRITE(stg) do { \
;         _Pragma("unroll") for (int i_ = 0; i_ < 4; ++i_) { const int pid_ = tid + 512 * i_, row_ = pid_ >> 4, c16_ = pid_ & 15; \
;             *(LAS u32x4*)(lds + (stg) * A_STAGE + A_KOFF + row_ * AK_PITCH + 16 * c16_) = preK[i_]; *(LAS u32x4*)(lds + (stg) * A_STAGE + A_VOFF + row_ * AV_PITCH + 16 * c16_) = preV[i_]; } \
;     } while (0)
; __device__ __forceinline__ void attn_unit(const PT& p, LAS unsigned char* lds, int tid, int lane, int wave, int b, int hd, int qb, float lam) {
;     ...
;     const int qw0 = qb * 128 + 32 * wq, q = qw0 + r32; const unsigned tokq = (unsigned)(b * SEQ + q), tokb = (unsigned)(b * SEQ);
;     const float slope2 = fexp2(-0.5f * (float)(hd + 1)) * LOG2E;
;     bf16x8 qf[4];
; #pragma unroll
;     for (int ds = 0; ds < 4; ++ds) qf[ds] = ld_frag16(Qb + (tokq * 2048u + (unsigned)(hd * 128 + mp * 64 + 16 * ds + 8 * h)));
;     float mrun = -INFINITY, lsum = 0.f;
;     f32x16 oT[4];
; #pragma unroll
;     for (int db = 0; db < 4; ++db)
; #pragma unroll
;         for (int i = 0; i < 16; ++i) oT[db][i] = 0.f;
;     const int ntiles = qb + 1;
;     u32x4 preV[4], preK[4];
;     ...
;     PREFETCH(0);
;     const LAS unsigned char* kbase0 = lds + A_KOFF + r32 * AK_PITCH + (mp * 64 + 8 * h) * 2;
;     const LAS unsigned char* vbase0 = lds + A_VOFF + (4 * h + ((lane & 15) >> 2)) * AV_PITCH + ((lane >> 4) & 1) * 32 + (lane & 3) * 8;
;     ...
;     __syncthreads();
;     STAGE_WRITE(0);
;     asm volatile("" : "+v"(qf[0]), "+v"(qf[1]), "+v"(qf[2]), "+v"(qf[3]));
;     __syncthreads();
.LBB0_1074:
	s_xor_b64 s[76:77], s[36:37], -1
	s_and_b64 s[36:37], s[36:37], exec
	s_cselect_b32 s95, s93, s92
	v_lshl_or_b32 v8, s95, 7, v228
	v_or_b32_e32 v0, s94, v8
	v_lshlrev_b32_e32 v241, 11, v0
	v_add_u32_e32 v50, v239, v241
	v_lshl_add_u64 v[0:1], v[50:51], 1, s[40:41]
	v_or_b32_e32 v2, 16, v50
	v_mov_b32_e32 v3, v51
	v_or_b32_e32 v4, 32, v50
	v_mov_b32_e32 v5, v51
	v_or_b32_e32 v50, 48, v50
	v_lshl_add_u64 v[2:3], v[2:3], 1, s[40:41]
	v_lshl_add_u64 v[4:5], v[4:5], 1, s[40:41]
	v_lshl_add_u64 v[6:7], v[50:51], 1, s[40:41]
	s_lshl_b32 s96, s95, 18
	s_sub_i32 s99, s96, 0x40000
	v_add_u32_e32 v50, s99, v238
	v_lshlrev_b64 v[52:53], 1, v[50:51]
	v_lshl_add_u64 v[54:55], s[46:47], 0, v[52:53]
	v_lshl_add_u64 v[52:53], s[42:43], 0, v[52:53]
	global_load_dwordx4 v[134:137], v[54:55], off
	global_load_dwordx4 v[138:141], v[52:53], off
	v_add_u32_e32 v50, s99, v237
	v_lshlrev_b64 v[52:53], 1, v[50:51]
	v_lshl_add_u64 v[54:55], s[46:47], 0, v[52:53]
	v_lshl_add_u64 v[52:53], s[42:43], 0, v[52:53]
	global_load_dwordx4 v[154:157], v[54:55], off
	global_load_dwordx4 v[158:161], v[52:53], off
	v_add_u32_e32 v50, s99, v236
	v_lshlrev_b64 v[52:53], 1, v[50:51]
	v_lshl_add_u64 v[54:55], s[46:47], 0, v[52:53]
	v_lshl_add_u64 v[52:53], s[42:43], 0, v[52:53]
	global_load_dwordx4 v[162:165], v[54:55], off
	global_load_dwordx4 v[166:169], v[52:53], off
	v_add_u32_e32 v50, s99, v235
	v_lshlrev_b64 v[52:53], 1, v[50:51]
	v_lshl_add_u64 v[54:55], s[46:47], 0, v[52:53]
	v_lshl_add_u64 v[52:53], s[42:43], 0, v[52:53]
	global_load_dwordx4 v[170:173], v[54:55], off
	global_load_dwordx4 v[174:177], v[52:53], off
	global_load_dwordx4 v[130:133], v[0:1], off
	global_load_dwordx4 v[142:145], v[6:7], off
	global_load_dwordx4 v[146:149], v[4:5], off
	global_load_dwordx4 v[150:153], v[2:3], off
	v_add_u32_e32 v0, v206, v207
	s_barrier
	v_mov_b32_e32 v64, v51
	v_mov_b32_e32 v65, v51
	s_lshl_b32 s96, s95, 18
	v_mov_b32_e32 v50, v51
	v_mov_b32_e32 v52, v51
	v_mov_b32_e32 v53, v51
	v_mov_b32_e32 v54, v51
	v_mov_b32_e32 v55, v51
	v_mov_b32_e32 v56, v51
	v_mov_b32_e32 v57, v51
	v_mov_b32_e32 v58, v51
	v_mov_b32_e32 v59, v51
	v_mov_b32_e32 v60, v51
	v_mov_b32_e32 v61, v51
	v_mov_b32_e32 v62, v51
	v_mov_b32_e32 v63, v51
	v_mov_b64_e32 v[80:81], v[64:65]
	v_mov_b64_e32 v[96:97], v[64:65]
	v_mov_b64_e32 v[112:113], v[64:65]
	v_mov_b64_e32 v[128:129], v[64:65]
	v_sub_u32_e32 v242, v178, v8
	v_lshl_add_u32 v242, s95, 7, v242
	s_mov_b32 s97, 0xfffc0000
	s_mov_b32 s38, s96
	v_mov_b32_e32 v248, 0xff800000
	s_mov_b64 s[100:101], -1
	v_mov_b32_e32 v243, 0
	v_mov_b64_e32 v[78:79], v[62:63]
	v_mov_b64_e32 v[76:77], v[60:61]
	v_mov_b64_e32 v[74:75], v[58:59]
	v_mov_b64_e32 v[72:73], v[56:57]
	v_mov_b64_e32 v[70:71], v[54:55]
	v_mov_b64_e32 v[68:69], v[52:53]
	v_mov_b64_e32 v[66:67], v[50:51]
	v_mov_b64_e32 v[94:95], v[62:63]
	v_mov_b64_e32 v[92:93], v[60:61]
	v_mov_b64_e32 v[90:91], v[58:59]
	v_mov_b64_e32 v[88:89], v[56:57]
	v_mov_b64_e32 v[86:87], v[54:55]
	v_mov_b64_e32 v[84:85], v[52:53]
	v_mov_b64_e32 v[82:83], v[50:51]
	v_mov_b64_e32 v[110:111], v[62:63]
	v_mov_b64_e32 v[108:109], v[60:61]
	v_mov_b64_e32 v[106:107], v[58:59]
	v_mov_b64_e32 v[104:105], v[56:57]
	v_mov_b64_e32 v[102:103], v[54:55]
	v_mov_b64_e32 v[100:101], v[52:53]
	v_mov_b64_e32 v[98:99], v[50:51]
	v_mov_b64_e32 v[126:127], v[62:63]
	v_mov_b64_e32 v[124:125], v[60:61]
	v_mov_b64_e32 v[122:123], v[58:59]
	v_mov_b64_e32 v[120:121], v[56:57]
	v_mov_b64_e32 v[118:119], v[54:55]
	v_mov_b64_e32 v[116:117], v[52:53]
	v_mov_b64_e32 v[114:115], v[50:51]
	s_mov_b32 s39, 0
	s_waitcnt vmcnt(11)
	ds_write_b128 v0, v[134:137]
	s_waitcnt vmcnt(10)
	v_bfe_u32 v2, v196, 4, 2
	v_bfe_u32 v3, v196, 6, 2
	v_sub_u32_e32 v2, v2, v3
	v_mul_i32_i24_e32 v2, 0x330, v2
	v_add_u32_e32 v3, v2, v0
	ds_write_b128 v3, v[138:141] offset:34816
	v_add_u32_e32 v0, v206, v208
	s_waitcnt vmcnt(9)
	ds_write_b128 v0, v[154:157]
	s_waitcnt vmcnt(8)
	v_add_u32_e32 v3, v2, v0
	ds_write_b128 v3, v[158:161] offset:34816
	v_add_u32_e32 v0, v206, v209
	s_waitcnt vmcnt(7)
	ds_write_b128 v0, v[162:165]
	s_waitcnt vmcnt(6)
	v_add_u32_e32 v3, v2, v0
	ds_write_b128 v3, v[166:169] offset:34816
	v_add_u32_e32 v0, v206, v210
	s_waitcnt vmcnt(5)
	ds_write_b128 v0, v[170:173]
	s_waitcnt vmcnt(4)
	v_add_u32_e32 v3, v2, v0
	ds_write_b128 v3, v[174:177] offset:34816
	s_waitcnt vmcnt(0)
	s_waitcnt lgkmcnt(0)
	s_barrier
	s_branch .LBB0_1076

; #define LAS __attribute__((address_space(3)))
; __device__ __forceinline__ f32x16 mfma32(bf16x8 a, bf16x8 b, f32x16 c) { return __builtin_amdgcn_mfma_f32_32x32x16_bf16(a, b, c, 0, 0, 0); }
; __device__ __forceinline__ void attn_unit(const PT& p, LAS unsigned char* lds, int tid, int lane, int wave, int b, int hd, int qb, float lam) {
;     ...
;         for (int sub = 0; sub < 2; ++sub) {
;             const int nact = diag ? min(2, max(0, wq + 1 - 2 * sub)) : 2;
;             if (nact > 0) {
;                 float sl = slope2; asm volatile("" : "+v"(sl));
;                 const float bq = sl * (float)(t * 128 + sub * 64 + 4 * h - q);
;                 const LAS unsigned char* kb0 = kbase + sub * 64 * AK_PITCH; const LAS unsigned char* vb0 = vbase + sub * 64 * AV_PITCH;
;                 f32x16 s[2];
; #pragma unroll
;                 for (int kb = 0; kb < 2; ++kb) {
;                     if (kb < nact) {
;                         const float bk = bq + sl * (float)(32 * kb);
; #pragma unroll
;                         for (int i = 0; i < 16; ++i) s[kb][i] = __builtin_fmaf(sl, (float)((i & 3) + 8 * (i >> 2)), bk);
; #pragma unroll
;                         for (int ds = 0; ds < 4; ++ds) s[kb] = mfma32(__builtin_bit_cast(bf16x8, *(const LAS u32x4*)(kb0 + kb * 32 * AK_PITCH + ds * 32)), qf[ds], s[kb]);
;                     } else {
; #pragma unroll
;                         for (int i = 0; i < 16; ++i) s[kb][i] = -INFINITY;
;                     }
;                 }
.Lat_nostagger:
	s_and_b64 s[36:37], s[82:83], exec
	s_cselect_b32 s36, 2, s33
	s_cmp_eq_u32 s36, 0
	s_cbranch_scc1 .Lat1_done
	s_cmp_lg_u32 s36, 1
	s_cselect_b64 s[36:37], -1, 0
	ds_read_b128 v[0:3], v56 offset:17408
	ds_read_b128 v[4:7], v56 offset:17440
	ds_read_b128 v[8:11], v56 offset:17472
	ds_read_b128 v[12:15], v56 offset:17504
	v_add_u32_e32 v50, 64, v242
	v_cvt_f32_i32_e32 v50, v50
	v_cndmask_b32_e64 v52, v248, 0, s[100:101]
	v_fma_f32 v255, v240, v50, -v52
	v_mov_b32_e32 v18, v255
	v_add_f32_e32 v19, v240, v255
	v_fma_f32 v20, v240, s62, v255
	v_fma_f32 v21, v240, s63, v255
	v_fma_f32 v22, v240, s64, v255
	v_fma_f32 v23, v240, s65, v255
	v_fma_f32 v24, v240, s66, v255
	v_fma_f32 v25, v240, s67, v255
	v_fma_f32 v26, v240, s68, v255
	v_fma_f32 v27, v240, s69, v255
	v_fma_f32 v28, v240, s70, v255
	v_fma_f32 v29, v240, s71, v255
	v_fma_f32 v30, v240, s72, v255
	v_fma_f32 v31, v240, s73, v255
	v_fma_f32 v32, v240, s74, v255
	v_fma_f32 v33, v240, s75, v255
	s_andn2_b64 vcc, exec, s[36:37]
	s_cbranch_vccnz .Lat1_k1off
	ds_read_b128 v[250:253], v56 offset:26112
	ds_read_b128 v[244:247], v56 offset:26144
	s_waitcnt lgkmcnt(5)
	v_mfma_f32_32x32x16_bf16 v[18:33], v[0:3], v[130:133], v[18:33]
	ds_read_b128 v[0:3], v56 offset:26176
	v_fmac_f32_e32 v255, 0x42000000, v240
	v_mov_b32_e32 v34, v255
	v_add_f32_e32 v35, v240, v255
	v_fma_f32 v36, v240, s62, v255
	v_fma_f32 v37, v240, s63, v255
	v_fma_f32 v38, v240, s64, v255
	s_waitcnt lgkmcnt(5)
	v_mfma_f32_32x32x16_bf16 v[18:33], v[4:7], v[150:153], v[18:33]
	ds_read_b128 v[4:7], v56 offset:26208
	v_fma_f32 v39, v240, s65, v255
	v_fma_f32 v40, v240, s66, v255
	v_fma_f32 v41, v240, s67, v255
	v_fma_f32 v42, v240, s68, v255
	v_fma_f32 v43, v240, s69, v255
	v_fma_f32 v44, v240, s70, v255
	s_waitcnt lgkmcnt(5)
	v_mfma_f32_32x32x16_bf16 v[18:33], v[8:11], v[146:149], v[18:33]
	v_fma_f32 v45, v240, s71, v255
	v_fma_f32 v46, v240, s72, v255
	v_fma_f32 v47, v240, s73, v255
	v_fma_f32 v48, v240, s74, v255
	v_fma_f32 v49, v240, s75, v255
	s_waitcnt lgkmcnt(4)
	v_mfma_f32_32x32x16_bf16 v[18:33], v[12:15], v[142:145], v[18:33]
	s_waitcnt lgkmcnt(3)
	v_mfma_f32_32x32x16_bf16 v[34:49], v[250:253], v[130:133], v[34:49]
	s_waitcnt lgkmcnt(2)
	v_mfma_f32_32x32x16_bf16 v[34:49], v[244:247], v[150:153], v[34:49]
	s_waitcnt lgkmcnt(1)
	v_mfma_f32_32x32x16_bf16 v[34:49], v[0:3], v[146:149], v[34:49]
	s_waitcnt lgkmcnt(0)
	v_mfma_f32_32x32x16_bf16 v[34:49], v[4:7], v[142:145], v[34:49]
	s_branch .Lat1_qkdone

; #define LAS __attribute__((address_space(3)))
; __device__ __forceinline__ float fexp2(float x) { return __builtin_amdgcn_exp2f(x); }
; __device__ __forceinline__ float max3f(float a, float b, float c) { return fmaxf(fmaxf(a, b), c); }
; __device__ __forceinline__ void attn_unit(const PT& p, LAS unsigned char* lds, int tid, int lane, int wave, int b, int hd, int qb, float lam) {
;     ...
;                 float mx = -INFINITY;
; #pragma unroll
;                 for (int kb = 0; kb < 2; ++kb)
; #pragma unroll
;                     for (int i = 0; i < 16; i += 2) mx = max3f(mx, s[kb][i], s[kb][i + 1]);
;                 mx = fmaxf(mx, __shfl_xor(mx, 32));
;                 const float mnew = fmaxf(mrun, mx), alpha = fexp2(mrun - mnew); mrun = mnew;
;                 float rs0 = 0.f, rs1 = 0.f, rs2 = 0.f, rs3 = 0.f;
; #pragma unroll
;                 for (int kb = 0; kb < 2; ++kb)
; #pragma unroll
;                     for (int i = 0; i < 16; i += 4) { s[kb][i] = fexp2(s[kb][i] - mnew); s[kb][i + 1] = fexp2(s[kb][i + 1] - mnew); s[kb][i + 2] = fexp2(s[kb][i + 2] - mnew); s[kb][i + 3] = fexp2(s[kb][i + 3] - mnew);
;                         rs0 += s[kb][i]; rs1 += s[kb][i + 1]; rs2 += s[kb][i + 2]; rs3 += s[kb][i + 3]; }
;                 lsum = lsum * alpha + ((rs0 + rs1) + (rs2 + rs3));
;                 if (__builtin_amdgcn_ballot_w64(alpha != 1.0f) != 0ull) {
; #pragma unroll
;                     for (int db = 0; db < 4; ++db)
; #pragma unroll
;                         for (int i = 0; i < 16; ++i) oT[db][i] *= alpha;
;                 }
; #pragma unroll
;                 for (int kb = 0; kb < 2; ++kb) if (kb < nact) {
; #pragma unroll
;                     for (int s2 = 0; s2 < 2; ++s2) {
;                         const bf16x8 pf = pack_frag(s[kb], s2);
; #pragma unroll
;                         for (int db = 0; db < 4; ++db) {
;                             const LAS unsigned char* vp = vb0 + (kb * 32 + 16 * s2) * AV_PITCH + db * 64;
;                             const v4i16_t lo = __builtin_amdgcn_ds_read_tr16_b64_v4i16((LAS v4i16_t*)vp), hi = __builtin_amdgcn_ds_read_tr16_b64_v4i16((LAS v4i16_t*)(vp + 8 * AV_PITCH));
;                             const bf16x8 vf = {lo[0], lo[1], lo[2], lo[3], hi[0], hi[1], hi[2], hi[3]};
;                             oT[db] = mfma32(vf, pf, oT[db]);
;                         }
;                     }
;                 }
.Lat1_nodiag:
	ds_read_b64_tr_b16 v[250:251], v254 offset:17408
	ds_read_b64_tr_b16 v[252:253], v254 offset:17952
	ds_read_b64_tr_b16 v[244:245], v254 offset:17472
	ds_read_b64_tr_b16 v[246:247], v254 offset:18016
	s_nop 1
	v_max3_f32 v0, v18, s89, v19
	v_max3_f32 v0, v0, v20, v21
	v_max3_f32 v0, v0, v22, v23
	v_max3_f32 v0, v0, v24, v25
	v_max3_f32 v0, v0, v26, v27
	v_max3_f32 v0, v0, v28, v29
	v_max3_f32 v0, v0, v30, v31
	v_max3_f32 v0, v0, v32, v33
	v_max3_f32 v0, v0, v34, v35
	v_max3_f32 v0, v0, v36, v37
	v_max3_f32 v0, v0, v38, v39
	v_max3_f32 v0, v0, v40, v41
	v_max3_f32 v0, v0, v42, v43
	v_max3_f32 v0, v0, v44, v45
	v_max3_f32 v0, v0, v46, v47
	v_max3_f32 v0, v0, v48, v49
	v_mov_b32_e32 v1, v0
	s_nop 1
	v_permlane32_swap_b32_e32 v0, v1
	v_max_f32_e32 v0, v0, v1
	s_cmp_lg_u64 s[100:101], 0
	s_cbranch_scc1 .Lat1_slow
	v_cmp_ngt_f32_e32 vcc, 0xc3160000, v0
	s_cbranch_vccz .Lat1_zskip
	v_cmp_lt_f32_e32 vcc, 0, v0
	s_cbranch_vccnz .Lat1_slow
.Lat1_fast:
	v_exp_f32_e32 v1, v18
	v_exp_f32_e32 v2, v19
	v_exp_f32_e32 v3, v20
	v_exp_f32_e32 v4, v21
	v_exp_f32_e32 v5, v22
	v_exp_f32_e32 v6, v23
	v_exp_f32_e32 v7, v24
	v_exp_f32_e32 v8, v25
	v_exp_f32_e32 v22, v38
	v_exp_f32_e32 v23, v39
	v_exp_f32_e32 v24, v40
	v_exp_f32_e32 v25, v41
	ds_read_b64_tr_b16 v[38:39], v254 offset:17536
	ds_read_b64_tr_b16 v[40:41], v254 offset:18080
	v_exp_f32_e32 v18, v34
	v_exp_f32_e32 v19, v35
	v_exp_f32_e32 v20, v36
	v_exp_f32_e32 v21, v37
	v_cvt_pk_bf16_f32 v34, v1, v2
	v_cvt_pk_bf16_f32 v35, v3, v4
	v_cvt_pk_bf16_f32 v36, v5, v6
	v_cvt_pk_bf16_f32 v37, v7, v8
	s_nop 0
	s_waitcnt lgkmcnt(4)
	v_mfma_f32_32x32x16_bf16 v[114:129], v[250:253], v[34:37], v[114:129]
	ds_read_b64_tr_b16 v[250:251], v254 offset:17600
	ds_read_b64_tr_b16 v[252:253], v254 offset:18144
	v_exp_f32_e32 v9, v26
	v_exp_f32_e32 v10, v27
	v_exp_f32_e32 v11, v28
	s_waitcnt lgkmcnt(4)
	v_mfma_f32_32x32x16_bf16 v[98:113], v[244:247], v[34:37], v[98:113]
	ds_read_b64_tr_b16 v[244:245], v254 offset:21760
	ds_read_b64_tr_b16 v[246:247], v254 offset:22304
	v_exp_f32_e32 v12, v29
	v_exp_f32_e32 v13, v30
	v_exp_f32_e32 v14, v31
	s_waitcnt lgkmcnt(4)
	v_mfma_f32_32x32x16_bf16 v[82:97], v[38:41], v[34:37], v[82:97]
	ds_read_b64_tr_b16 v[38:39], v254 offset:21824
	ds_read_b64_tr_b16 v[40:41], v254 offset:22368
	v_exp_f32_e32 v15, v32
	v_exp_f32_e32 v17, v33
	s_waitcnt lgkmcnt(4)
	v_mfma_f32_32x32x16_bf16 v[66:81], v[250:253], v[34:37], v[66:81]
	ds_read_b64_tr_b16 v[250:251], v254 offset:21888
	ds_read_b64_tr_b16 v[252:253], v254 offset:22432
	v_cvt_pk_bf16_f32 v34, v9, v10
	v_cvt_pk_bf16_f32 v35, v11, v12
	v_cvt_pk_bf16_f32 v36, v13, v14
	v_cvt_pk_bf16_f32 v37, v15, v17
	v_exp_f32_e32 v26, v42
	s_waitcnt lgkmcnt(4)
	v_mfma_f32_32x32x16_bf16 v[114:129], v[244:247], v[34:37], v[114:129]
	ds_read_b64_tr_b16 v[244:245], v254 offset:21952
	ds_read_b64_tr_b16 v[246:247], v254 offset:22496
	v_exp_f32_e32 v27, v43
	v_exp_f32_e32 v28, v44
	v_exp_f32_e32 v29, v45
	s_waitcnt lgkmcnt(4)
	v_mfma_f32_32x32x16_bf16 v[98:113], v[38:41], v[34:37], v[98:113]
	ds_read_b64_tr_b16 v[38:39], v254 offset:26112
	ds_read_b64_tr_b16 v[40:41], v254 offset:26656
	v_exp_f32_e32 v30, v46
	v_exp_f32_e32 v31, v47
	v_exp_f32_e32 v32, v48
	s_waitcnt lgkmcnt(4)
	v_mfma_f32_32x32x16_bf16 v[82:97], v[250:253], v[34:37], v[82:97]
	ds_read_b64_tr_b16 v[250:251], v254 offset:26176
	ds_read_b64_tr_b16 v[252:253], v254 offset:26720
	v_exp_f32_e32 v33, v49
	v_add_f32_e32 v1, v5, v1
	v_add_f32_e32 v2, v6, v2
	v_add_f32_e32 v3, v7, v3
	v_add_f32_e32 v4, v8, v4
	s_waitcnt lgkmcnt(4)
	v_mfma_f32_32x32x16_bf16 v[66:81], v[244:247], v[34:37], v[66:81]
	ds_read_b64_tr_b16 v[244:245], v254 offset:26240
	ds_read_b64_tr_b16 v[246:247], v254 offset:26784
	s_andn2_b64 vcc, exec, s[36:37]
	s_cbranch_vccnz .Lat1_pvk1off
	v_cvt_pk_bf16_f32 v34, v18, v19
	v_cvt_pk_bf16_f32 v35, v20, v21
	v_cvt_pk_bf16_f32 v36, v22, v23
	v_cvt_pk_bf16_f32 v37, v24, v25
	s_nop 0
	s_waitcnt lgkmcnt(4)
	v_mfma_f32_32x32x16_bf16 v[114:129], v[38:41], v[34:37], v[114:129]
	ds_read_b64_tr_b16 v[38:39], v254 offset:26304
	ds_read_b64_tr_b16 v[40:41], v254 offset:26848
	v_add_f32_e32 v1, v9, v1
	v_add_f32_e32 v2, v10, v2
	v_add_f32_e32 v3, v11, v3
	v_add_f32_e32 v4, v12, v4
	s_waitcnt lgkmcnt(4)
	v_mfma_f32_32x32x16_bf16 v[98:113], v[250:253], v[34:37], v[98:113]
	ds_read_b64_tr_b16 v[250:251], v254 offset:30464
	ds_read_b64_tr_b16 v[252:253], v254 offset:31008
	v_add_f32_e32 v1, v13, v1
	v_add_f32_e32 v2, v14, v2
	v_add_f32_e32 v3, v15, v3
	v_add_f32_e32 v4, v17, v4
	s_waitcnt lgkmcnt(4)
	v_mfma_f32_32x32x16_bf16 v[82:97], v[244:247], v[34:37], v[82:97]
	ds_read_b64_tr_b16 v[244:245], v254 offset:30528
	ds_read_b64_tr_b16 v[246:247], v254 offset:31072
	v_add_f32_e32 v1, v18, v1
	v_add_f32_e32 v2, v19, v2
	v_add_f32_e32 v3, v20, v3
	v_add_f32_e32 v4, v21, v4
	s_waitcnt lgkmcnt(4)
	v_mfma_f32_32x32x16_bf16 v[66:81], v[38:41], v[34:37], v[66:81]
	ds_read_b64_tr_b16 v[38:39], v254 offset:30592
	ds_read_b64_tr_b16 v[40:41], v254 offset:31136
	v_cvt_pk_bf16_f32 v34, v26, v27
	v_cvt_pk_bf16_f32 v35, v28, v29
	v_cvt_pk_bf16_f32 v36, v30, v31
	v_cvt_pk_bf16_f32 v37, v32, v33
	s_nop 0
	s_waitcnt lgkmcnt(4)
	v_mfma_f32_32x32x16_bf16 v[114:129], v[250:253], v[34:37], v[114:129]
	ds_read_b64_tr_b16 v[250:251], v254 offset:30656
	ds_read_b64_tr_b16 v[252:253], v254 offset:31200
	v_add_f32_e32 v1, v22, v1
	v_add_f32_e32 v2, v23, v2
	v_add_f32_e32 v3, v24, v3
	v_add_f32_e32 v4, v25, v4
	s_waitcnt lgkmcnt(4)
	v_mfma_f32_32x32x16_bf16 v[98:113], v[244:247], v[34:37], v[98:113]
	v_add_f32_e32 v1, v26, v1
	v_add_f32_e32 v2, v27, v2
	v_add_f32_e32 v3, v28, v3
	v_add_f32_e32 v4, v29, v4
	s_waitcnt lgkmcnt(2)
	v_mfma_f32_32x32x16_bf16 v[82:97], v[38:41], v[34:37], v[82:97]
	v_add_f32_e32 v1, v30, v1
	v_add_f32_e32 v2, v31, v2
	v_add_f32_e32 v3, v32, v3
	v_add_f32_e32 v4, v33, v4
	s_waitcnt lgkmcnt(0)
	v_mfma_f32_32x32x16_bf16 v[66:81], v[250:253], v[34:37], v[66:81]
	v_add_f32_e32 v1, v1, v2
	v_add_f32_e32 v2, v3, v4
	v_add_f32_e32 v1, v1, v2
	v_add_f32_e32 v243, v243, v1
	s_branch .Lat1_done
; #define LAS __attribute__((address_space(3)))
; __device__ __forceinline__ float fexp2(float x) { return __builtin_amdgcn_exp2f(x); }
; __device__ __forceinline__ float max3f(float a, float b, float c) { return fmaxf(fmaxf(a, b), c); }
; __device__ __forceinline__ void attn_unit(const PT& p, LAS unsigned char* lds, int tid, int lane, int wave, int b, int hd, int qb, float lam) {
;     ...
;                 float mx = -INFINITY;
; #pragma unroll
;                 for (int kb = 0; kb < 2; ++kb)
; #pragma unroll
;                     for (int i = 0; i < 16; i += 2) mx = max3f(mx, s[kb][i], s[kb][i + 1]);
;                 mx = fmaxf(mx, __shfl_xor(mx, 32));
;                 const float mnew = fmaxf(mrun, mx), alpha = fexp2(mrun - mnew); mrun = mnew;
;                 float rs0 = 0.f, rs1 = 0.f, rs2 = 0.f, rs3 = 0.f;
; #pragma unroll
;                 for (int kb = 0; kb < 2; ++kb)
; #pragma unroll
;                     for (int i = 0; i < 16; i += 4) { s[kb][i] = fexp2(s[kb][i] - mnew); s[kb][i + 1] = fexp2(s[kb][i + 1] - mnew); s[kb][i + 2] = fexp2(s[kb][i + 2] - mnew); s[kb][i + 3] = fexp2(s[kb][i + 3] - mnew);
;                         rs0 += s[kb][i]; rs1 += s[kb][i + 1]; rs2 += s[kb][i + 2]; rs3 += s[kb][i + 3]; }
;                 lsum = lsum * alpha + ((rs0 + rs1) + (rs2 + rs3));
;                 if (__builtin_amdgcn_ballot_w64(alpha != 1.0f) != 0ull) {
; #pragma unroll
;                     for (int db = 0; db < 4; ++db)
; #pragma unroll
;                         for (int i = 0; i < 16; ++i) oT[db][i] *= alpha;
;                 }
; #pragma unroll
;                 for (int kb = 0; kb < 2; ++kb) if (kb < nact) {
; #pragma unroll
;                     for (int s2 = 0; s2 < 2; ++s2) {
;                         const bf16x8 pf = pack_frag(s[kb], s2);
; #pragma unroll
;                         for (int db = 0; db < 4; ++db) {
;                             const LAS unsigned char* vp = vb0 + (kb * 32 + 16 * s2) * AV_PITCH + db * 64;
;                             const v4i16_t lo = __builtin_amdgcn_ds_read_tr16_b64_v4i16((LAS v4i16_t*)vp), hi = __builtin_amdgcn_ds_read_tr16_b64_v4i16((LAS v4i16_t*)(vp + 8 * AV_PITCH));
;                             const bf16x8 vf = {lo[0], lo[1], lo[2], lo[3], hi[0], hi[1], hi[2], hi[3]};
;                             oT[db] = mfma32(vf, pf, oT[db]);
;                         }
;                     }
;                 }
.Lat1_pvk1off:
	s_waitcnt lgkmcnt(0)
	v_add_f32_e32 v1, v9, v1
	v_add_f32_e32 v2, v10, v2
	v_add_f32_e32 v3, v11, v3
	v_add_f32_e32 v4, v12, v4
	v_add_f32_e32 v1, v13, v1
	v_add_f32_e32 v2, v14, v2
	v_add_f32_e32 v3, v15, v3
	v_add_f32_e32 v4, v17, v4
	v_add_f32_e32 v1, v18, v1
	v_add_f32_e32 v2, v19, v2
	v_add_f32_e32 v3, v20, v3
	v_add_f32_e32 v4, v21, v4
	v_add_f32_e32 v1, v22, v1
	v_add_f32_e32 v2, v23, v2
	v_add_f32_e32 v3, v24, v3
	v_add_f32_e32 v4, v25, v4
	v_add_f32_e32 v1, v26, v1
	v_add_f32_e32 v2, v27, v2
	v_add_f32_e32 v3, v28, v3
	v_add_f32_e32 v4, v29, v4
	v_add_f32_e32 v1, v30, v1
	v_add_f32_e32 v2, v31, v2
	v_add_f32_e32 v3, v32, v3
	v_add_f32_e32 v4, v33, v4
	v_add_f32_e32 v1, v1, v2
	v_add_f32_e32 v2, v3, v4
	v_add_f32_e32 v1, v1, v2
	v_add_f32_e32 v243, v243, v1
	s_branch .Lat1_done
.Lat1_slow:
	s_cmp_lg_u64 s[100:101], 0
	s_cbranch_scc1 .Lat1_slow_first
	v_max_f32_e32 v0, 0, v0
	v_sub_f32_e32 v18, v18, v0
	v_sub_f32_e32 v19, v19, v0
	v_sub_f32_e32 v20, v20, v0
	v_sub_f32_e32 v21, v21, v0
	v_sub_f32_e32 v22, v22, v0
	v_sub_f32_e32 v23, v23, v0
	v_sub_f32_e32 v24, v24, v0
	v_sub_f32_e32 v25, v25, v0
	v_sub_f32_e32 v26, v26, v0
	v_sub_f32_e32 v27, v27, v0
	v_sub_f32_e32 v28, v28, v0
	v_sub_f32_e32 v29, v29, v0
	v_sub_f32_e32 v30, v30, v0
	v_sub_f32_e32 v31, v31, v0
	v_sub_f32_e32 v32, v32, v0
	v_sub_f32_e32 v33, v33, v0
	v_sub_f32_e32 v34, v34, v0
	v_sub_f32_e32 v35, v35, v0
	v_sub_f32_e32 v36, v36, v0
	v_sub_f32_e32 v37, v37, v0
	v_sub_f32_e32 v38, v38, v0
	v_sub_f32_e32 v39, v39, v0
	v_sub_f32_e32 v40, v40, v0
	v_sub_f32_e32 v41, v41, v0
	v_sub_f32_e32 v42, v42, v0
	v_sub_f32_e32 v43, v43, v0
	v_sub_f32_e32 v44, v44, v0
	v_sub_f32_e32 v45, v45, v0
	v_sub_f32_e32 v46, v46, v0
	v_sub_f32_e32 v47, v47, v0
	v_sub_f32_e32 v48, v48, v0
	v_sub_f32_e32 v49, v49, v0
	v_add_f32_e32 v248, v52, v0
	v_sub_f32_e32 v0, 0, v0
	v_exp_f32_e32 v0, v0
	s_nop 0
	v_mul_f32_e32 v243, v243, v0
	v_mul_f32_e32 v129, v0, v129
	v_mul_f32_e32 v128, v0, v128
	v_mul_f32_e32 v127, v0, v127
	v_mul_f32_e32 v126, v0, v126
	v_mul_f32_e32 v125, v0, v125
	v_mul_f32_e32 v124, v0, v124
	v_mul_f32_e32 v123, v0, v123
	v_mul_f32_e32 v122, v0, v122
	v_mul_f32_e32 v121, v0, v121
	v_mul_f32_e32 v120, v0, v120
	v_mul_f32_e32 v119, v0, v119
	v_mul_f32_e32 v118, v0, v118
	v_mul_f32_e32 v117, v0, v117
	v_mul_f32_e32 v116, v0, v116
	v_mul_f32_e32 v115, v0, v115
	v_mul_f32_e32 v114, v0, v114
	v_mul_f32_e32 v113, v0, v113
	v_mul_f32_e32 v112, v0, v112
	v_mul_f32_e32 v111, v0, v111
	v_mul_f32_e32 v110, v0, v110
	v_mul_f32_e32 v109, v0, v109
	v_mul_f32_e32 v108, v0, v108
	v_mul_f32_e32 v107, v0, v107
	v_mul_f32_e32 v106, v0, v106
	v_mul_f32_e32 v105, v0, v105
	v_mul_f32_e32 v104, v0, v104
	v_mul_f32_e32 v103, v0, v103
	v_mul_f32_e32 v102, v0, v102
	v_mul_f32_e32 v101, v0, v101
	v_mul_f32_e32 v100, v0, v100
	v_mul_f32_e32 v99, v0, v99
	v_mul_f32_e32 v98, v0, v98
	v_mul_f32_e32 v97, v0, v97
	v_mul_f32_e32 v96, v0, v96
	v_mul_f32_e32 v95, v0, v95
	v_mul_f32_e32 v94, v0, v94
	v_mul_f32_e32 v93, v0, v93
	v_mul_f32_e32 v92, v0, v92
	v_mul_f32_e32 v91, v0, v91
	v_mul_f32_e32 v90, v0, v90
	v_mul_f32_e32 v89, v0, v89
	v_mul_f32_e32 v88, v0, v88
	v_mul_f32_e32 v87, v0, v87
	v_mul_f32_e32 v86, v0, v86
	v_mul_f32_e32 v85, v0, v85
	v_mul_f32_e32 v84, v0, v84
	v_mul_f32_e32 v83, v0, v83
	v_mul_f32_e32 v82, v0, v82
	v_mul_f32_e32 v81, v0, v81
	v_mul_f32_e32 v80, v0, v80
	v_mul_f32_e32 v79, v0, v79
	v_mul_f32_e32 v78, v0, v78
	v_mul_f32_e32 v77, v0, v77
	v_mul_f32_e32 v76, v0, v76
	v_mul_f32_e32 v75, v0, v75
	v_mul_f32_e32 v74, v0, v74
	v_mul_f32_e32 v73, v0, v73
	v_mul_f32_e32 v72, v0, v72
	v_mul_f32_e32 v71, v0, v71
	v_mul_f32_e32 v70, v0, v70
	v_mul_f32_e32 v69, v0, v69
	v_mul_f32_e32 v68, v0, v68
	v_mul_f32_e32 v67, v0, v67
	v_mul_f32_e32 v66, v0, v66
	s_branch .Lat1_fast
.Lat1_slow_first:
	v_sub_f32_e32 v18, v18, v0
	v_sub_f32_e32 v19, v19, v0
	v_sub_f32_e32 v20, v20, v0
	v_sub_f32_e32 v21, v21, v0
	v_sub_f32_e32 v22, v22, v0
	v_sub_f32_e32 v23, v23, v0
	v_sub_f32_e32 v24, v24, v0
	v_sub_f32_e32 v25, v25, v0
	v_sub_f32_e32 v26, v26, v0
	v_sub_f32_e32 v27, v27, v0
	v_sub_f32_e32 v28, v28, v0
	v_sub_f32_e32 v29, v29, v0
	v_sub_f32_e32 v30, v30, v0
	v_sub_f32_e32 v31, v31, v0
	v_sub_f32_e32 v32, v32, v0
	v_sub_f32_e32 v33, v33, v0
	v_sub_f32_e32 v34, v34, v0
	v_sub_f32_e32 v35, v35, v0
	v_sub_f32_e32 v36, v36, v0
	v_sub_f32_e32 v37, v37, v0
	v_sub_f32_e32 v38, v38, v0
	v_sub_f32_e32 v39, v39, v0
	v_sub_f32_e32 v40, v40, v0
	v_sub_f32_e32 v41, v41, v0
	v_sub_f32_e32 v42, v42, v0
	v_sub_f32_e32 v43, v43, v0
	v_sub_f32_e32 v44, v44, v0
	v_sub_f32_e32 v45, v45, v0
	v_sub_f32_e32 v46, v46, v0
	v_sub_f32_e32 v47, v47, v0
	v_sub_f32_e32 v48, v48, v0
	v_sub_f32_e32 v49, v49, v0
	v_add_f32_e32 v248, v52, v0
	s_mov_b64 s[100:101], 0
	s_branch .Lat1_fast

; #define LAS __attribute__((address_space(3)))
; __device__ __forceinline__ f32x16 mfma32(bf16x8 a, bf16x8 b, f32x16 c) { return __builtin_amdgcn_mfma_f32_32x32x16_bf16(a, b, c, 0, 0, 0); }
; __device__ __forceinline__ void attn_unit(const PT& p, LAS unsigned char* lds, int tid, int lane, int wave, int b, int hd, int qb, float lam) {
;     ...
;         for (int sub = 0; sub < 2; ++sub) {
;             const int nact = diag ? min(2, max(0, wq + 1 - 2 * sub)) : 2;
;             if (nact > 0) {
;                 float sl = slope2; asm volatile("" : "+v"(sl));
;                 const float bq = sl * (float)(t * 128 + sub * 64 + 4 * h - q);
;                 const LAS unsigned char* kb0 = kbase + sub * 64 * AK_PITCH; const LAS unsigned char* vb0 = vbase + sub * 64 * AV_PITCH;
;                 f32x16 s[2];
; #pragma unroll
;                 for (int kb = 0; kb < 2; ++kb) {
;                     if (kb < nact) {
;                         const float bk = bq + sl * (float)(32 * kb);
; #pragma unroll
;                         for (int i = 0; i < 16; ++i) s[kb][i] = __builtin_fmaf(sl, (float)((i & 3) + 8 * (i >> 2)), bk);
; #pragma unroll
;                         for (int ds = 0; ds < 4; ++ds) s[kb] = mfma32(__builtin_bit_cast(bf16x8, *(const LAS u32x4*)(kb0 + kb * 32 * AK_PITCH + ds * 32)), qf[ds], s[kb]);
;                     } else {
; #pragma unroll
;                         for (int i = 0; i < 16; ++i) s[kb][i] = -INFINITY;
;                     }
;                 }
.Lat1_done:
	ds_read_b128 v[0:3], v56 offset:0
	ds_read_b128 v[4:7], v56 offset:32
	ds_read_b128 v[8:11], v56 offset:64
	ds_read_b128 v[12:15], v56 offset:96
	v_cvt_f32_i32_e32 v50, v242
	v_cndmask_b32_e64 v52, v248, 0, s[100:101]
	v_fma_f32 v255, v240, v50, -v52
	v_mov_b32_e32 v18, v255
	v_add_f32_e32 v19, v240, v255
	v_fma_f32 v20, v240, s62, v255
	v_fma_f32 v21, v240, s63, v255
	v_fma_f32 v22, v240, s64, v255
	v_fma_f32 v23, v240, s65, v255
	v_fma_f32 v24, v240, s66, v255
	v_fma_f32 v25, v240, s67, v255
	v_fma_f32 v26, v240, s68, v255
	v_fma_f32 v27, v240, s69, v255
	v_fma_f32 v28, v240, s70, v255
	v_fma_f32 v29, v240, s71, v255
	v_fma_f32 v30, v240, s72, v255
	v_fma_f32 v31, v240, s73, v255
	v_fma_f32 v32, v240, s74, v255
	v_fma_f32 v33, v240, s75, v255
	s_andn2_b64 vcc, exec, s[84:85]
	s_cbranch_vccnz .Lat0_k1off
	ds_read_b128 v[250:253], v56 offset:8704
	ds_read_b128 v[244:247], v56 offset:8736
	s_waitcnt lgkmcnt(5)
	v_mfma_f32_32x32x16_bf16 v[18:33], v[0:3], v[130:133], v[18:33]
	ds_read_b128 v[0:3], v56 offset:8768
	v_fmac_f32_e32 v255, 0x42000000, v240
	v_mov_b32_e32 v34, v255
	v_add_f32_e32 v35, v240, v255
	v_fma_f32 v36, v240, s62, v255
	v_fma_f32 v37, v240, s63, v255
	v_fma_f32 v38, v240, s64, v255
	s_waitcnt lgkmcnt(5)
	v_mfma_f32_32x32x16_bf16 v[18:33], v[4:7], v[150:153], v[18:33]
	ds_read_b128 v[4:7], v56 offset:8800
	v_fma_f32 v39, v240, s65, v255
	v_fma_f32 v40, v240, s66, v255
	v_fma_f32 v41, v240, s67, v255
	v_fma_f32 v42, v240, s68, v255
	v_fma_f32 v43, v240, s69, v255
	v_fma_f32 v44, v240, s70, v255
	s_waitcnt lgkmcnt(5)
	v_mfma_f32_32x32x16_bf16 v[18:33], v[8:11], v[146:149], v[18:33]
	v_fma_f32 v45, v240, s71, v255
	v_fma_f32 v46, v240, s72, v255
	v_fma_f32 v47, v240, s73, v255
	v_fma_f32 v48, v240, s74, v255
	v_fma_f32 v49, v240, s75, v255
	s_waitcnt lgkmcnt(4)
	v_mfma_f32_32x32x16_bf16 v[18:33], v[12:15], v[142:145], v[18:33]
	s_waitcnt lgkmcnt(3)
	v_mfma_f32_32x32x16_bf16 v[34:49], v[250:253], v[130:133], v[34:49]
	s_waitcnt lgkmcnt(2)
	v_mfma_f32_32x32x16_bf16 v[34:49], v[244:247], v[150:153], v[34:49]
	s_waitcnt lgkmcnt(1)
	v_mfma_f32_32x32x16_bf16 v[34:49], v[0:3], v[146:149], v[34:49]
	s_waitcnt lgkmcnt(0)
	v_mfma_f32_32x32x16_bf16 v[34:49], v[4:7], v[142:145], v[34:49]
	s_branch .Lat0_qkdone

; #define LAS __attribute__((address_space(3)))
; __device__ __forceinline__ float fexp2(float x) { return __builtin_amdgcn_exp2f(x); }
; __device__ __forceinline__ float max3f(float a, float b, float c) { return fmaxf(fmaxf(a, b), c); }
; __device__ __forceinline__ void attn_unit(const PT& p, LAS unsigned char* lds, int tid, int lane, int wave, int b, int hd, int qb, float lam) {
;     ...
;                 float mx = -INFINITY;
; #pragma unroll
;                 for (int kb = 0; kb < 2; ++kb)
; #pragma unroll
;                     for (int i = 0; i < 16; i += 2) mx = max3f(mx, s[kb][i], s[kb][i + 1]);
;                 mx = fmaxf(mx, __shfl_xor(mx, 32));
;                 const float mnew = fmaxf(mrun, mx), alpha = fexp2(mrun - mnew); mrun = mnew;
;                 float rs0 = 0.f, rs1 = 0.f, rs2 = 0.f, rs3 = 0.f;
; #pragma unroll
;                 for (int kb = 0; kb < 2; ++kb)
; #pragma unroll
;                     for (int i = 0; i < 16; i += 4) { s[kb][i] = fexp2(s[kb][i] - mnew); s[kb][i + 1] = fexp2(s[kb][i + 1] - mnew); s[kb][i + 2] = fexp2(s[kb][i + 2] - mnew); s[kb][i + 3] = fexp2(s[kb][i + 3] - mnew);
;                         rs0 += s[kb][i]; rs1 += s[kb][i + 1]; rs2 += s[kb][i + 2]; rs3 += s[kb][i + 3]; }
;                 lsum = lsum * alpha + ((rs0 + rs1) + (rs2 + rs3));
;                 if (__builtin_amdgcn_ballot_w64(alpha != 1.0f) != 0ull) {
; #pragma unroll
;                     for (int db = 0; db < 4; ++db)
; #pragma unroll
;                         for (int i = 0; i < 16; ++i) oT[db][i] *= alpha;
;                 }
; #pragma unroll
;                 for (int kb = 0; kb < 2; ++kb) if (kb < nact) {
; #pragma unroll
;                     for (int s2 = 0; s2 < 2; ++s2) {
;                         const bf16x8 pf = pack_frag(s[kb], s2);
; #pragma unroll
;                         for (int db = 0; db < 4; ++db) {
;                             const LAS unsigned char* vp = vb0 + (kb * 32 + 16 * s2) * AV_PITCH + db * 64;
;                             const v4i16_t lo = __builtin_amdgcn_ds_read_tr16_b64_v4i16((LAS v4i16_t*)vp), hi = __builtin_amdgcn_ds_read_tr16_b64_v4i16((LAS v4i16_t*)(vp + 8 * AV_PITCH));
;                             const bf16x8 vf = {lo[0], lo[1], lo[2], lo[3], hi[0], hi[1], hi[2], hi[3]};
;                             oT[db] = mfma32(vf, pf, oT[db]);
;                         }
;                     }
;                 }
.Lat0_nodiag:
	ds_read_b64_tr_b16 v[250:251], v254 offset:0
	ds_read_b64_tr_b16 v[252:253], v254 offset:544
	ds_read_b64_tr_b16 v[244:245], v254 offset:64
	ds_read_b64_tr_b16 v[246:247], v254 offset:608
	s_nop 1
	v_max3_f32 v0, v18, s89, v19
	v_max3_f32 v0, v0, v20, v21
	v_max3_f32 v0, v0, v22, v23
	v_max3_f32 v0, v0, v24, v25
	v_max3_f32 v0, v0, v26, v27
	v_max3_f32 v0, v0, v28, v29
	v_max3_f32 v0, v0, v30, v31
	v_max3_f32 v0, v0, v32, v33
	v_max3_f32 v0, v0, v34, v35
	v_max3_f32 v0, v0, v36, v37
	v_max3_f32 v0, v0, v38, v39
	v_max3_f32 v0, v0, v40, v41
	v_max3_f32 v0, v0, v42, v43
	v_max3_f32 v0, v0, v44, v45
	v_max3_f32 v0, v0, v46, v47
	v_max3_f32 v0, v0, v48, v49
	v_mov_b32_e32 v1, v0
	s_nop 1
	v_permlane32_swap_b32_e32 v0, v1
	v_max_f32_e32 v0, v0, v1
	s_cmp_lg_u64 s[100:101], 0
	s_cbranch_scc1 .Lat0_slow
	v_cmp_ngt_f32_e32 vcc, 0xc3160000, v0
	s_cbranch_vccz .Lat0_zskip
	v_cmp_lt_f32_e32 vcc, 0, v0
	s_cbranch_vccnz .Lat0_slow
.Lat0_fast:
	v_exp_f32_e32 v1, v18
	v_exp_f32_e32 v2, v19
	v_exp_f32_e32 v3, v20
	v_exp_f32_e32 v4, v21
	v_exp_f32_e32 v5, v22
	v_exp_f32_e32 v6, v23
	v_exp_f32_e32 v7, v24
	v_exp_f32_e32 v8, v25
	v_exp_f32_e32 v22, v38
	v_exp_f32_e32 v23, v39
	v_exp_f32_e32 v24, v40
	v_exp_f32_e32 v25, v41
	ds_read_b64_tr_b16 v[38:39], v254 offset:128
	ds_read_b64_tr_b16 v[40:41], v254 offset:672
	v_exp_f32_e32 v18, v34
	v_exp_f32_e32 v19, v35
	v_exp_f32_e32 v20, v36
	v_exp_f32_e32 v21, v37
	v_cvt_pk_bf16_f32 v34, v1, v2
	v_cvt_pk_bf16_f32 v35, v3, v4
	v_cvt_pk_bf16_f32 v36, v5, v6
	v_cvt_pk_bf16_f32 v37, v7, v8
	s_nop 0
	s_waitcnt lgkmcnt(4)
	v_mfma_f32_32x32x16_bf16 v[114:129], v[250:253], v[34:37], v[114:129]
	ds_read_b64_tr_b16 v[250:251], v254 offset:192
	ds_read_b64_tr_b16 v[252:253], v254 offset:736
	v_exp_f32_e32 v9, v26
	v_exp_f32_e32 v10, v27
	v_exp_f32_e32 v11, v28
	s_waitcnt lgkmcnt(4)
	v_mfma_f32_32x32x16_bf16 v[98:113], v[244:247], v[34:37], v[98:113]
	ds_read_b64_tr_b16 v[244:245], v254 offset:4352
	ds_read_b64_tr_b16 v[246:247], v254 offset:4896
	v_exp_f32_e32 v12, v29
	v_exp_f32_e32 v13, v30
	v_exp_f32_e32 v14, v31
	s_waitcnt lgkmcnt(4)
	v_mfma_f32_32x32x16_bf16 v[82:97], v[38:41], v[34:37], v[82:97]
	ds_read_b64_tr_b16 v[38:39], v254 offset:4416
	ds_read_b64_tr_b16 v[40:41], v254 offset:4960
	v_exp_f32_e32 v15, v32
	v_exp_f32_e32 v17, v33
	s_waitcnt lgkmcnt(4)
	v_mfma_f32_32x32x16_bf16 v[66:81], v[250:253], v[34:37], v[66:81]
	ds_read_b64_tr_b16 v[250:251], v254 offset:4480
	ds_read_b64_tr_b16 v[252:253], v254 offset:5024
	v_cvt_pk_bf16_f32 v34, v9, v10
	v_cvt_pk_bf16_f32 v35, v11, v12
	v_cvt_pk_bf16_f32 v36, v13, v14
	v_cvt_pk_bf16_f32 v37, v15, v17
	v_exp_f32_e32 v26, v42
	s_waitcnt lgkmcnt(4)
	v_mfma_f32_32x32x16_bf16 v[114:129], v[244:247], v[34:37], v[114:129]
	ds_read_b64_tr_b16 v[244:245], v254 offset:4544
	ds_read_b64_tr_b16 v[246:247], v254 offset:5088
	v_exp_f32_e32 v27, v43
	v_exp_f32_e32 v28, v44
	v_exp_f32_e32 v29, v45
	s_waitcnt lgkmcnt(4)
	v_mfma_f32_32x32x16_bf16 v[98:113], v[38:41], v[34:37], v[98:113]
	ds_read_b64_tr_b16 v[38:39], v254 offset:8704
	ds_read_b64_tr_b16 v[40:41], v254 offset:9248
	v_exp_f32_e32 v30, v46
	v_exp_f32_e32 v31, v47
	v_exp_f32_e32 v32, v48
	s_waitcnt lgkmcnt(4)
	v_mfma_f32_32x32x16_bf16 v[82:97], v[250:253], v[34:37], v[82:97]
	ds_read_b64_tr_b16 v[250:251], v254 offset:8768
	ds_read_b64_tr_b16 v[252:253], v254 offset:9312
	v_exp_f32_e32 v33, v49
	v_add_f32_e32 v1, v5, v1
	v_add_f32_e32 v2, v6, v2
	v_add_f32_e32 v3, v7, v3
	v_add_f32_e32 v4, v8, v4
	s_waitcnt lgkmcnt(4)
	v_mfma_f32_32x32x16_bf16 v[66:81], v[244:247], v[34:37], v[66:81]
	ds_read_b64_tr_b16 v[244:245], v254 offset:8832
	ds_read_b64_tr_b16 v[246:247], v254 offset:9376
	s_andn2_b64 vcc, exec, s[84:85]
	s_cbranch_vccnz .Lat0_pvk1off
	v_cvt_pk_bf16_f32 v34, v18, v19
	v_cvt_pk_bf16_f32 v35, v20, v21
	v_cvt_pk_bf16_f32 v36, v22, v23
	v_cvt_pk_bf16_f32 v37, v24, v25
	s_nop 0
	s_waitcnt lgkmcnt(4)
	v_mfma_f32_32x32x16_bf16 v[114:129], v[38:41], v[34:37], v[114:129]
	ds_read_b64_tr_b16 v[38:39], v254 offset:8896
	ds_read_b64_tr_b16 v[40:41], v254 offset:9440
	v_add_f32_e32 v1, v9, v1
	v_add_f32_e32 v2, v10, v2
	v_add_f32_e32 v3, v11, v3
	v_add_f32_e32 v4, v12, v4
	s_waitcnt lgkmcnt(4)
	v_mfma_f32_32x32x16_bf16 v[98:113], v[250:253], v[34:37], v[98:113]
	ds_read_b64_tr_b16 v[250:251], v254 offset:13056
	ds_read_b64_tr_b16 v[252:253], v254 offset:13600
	v_add_f32_e32 v1, v13, v1
	v_add_f32_e32 v2, v14, v2
	v_add_f32_e32 v3, v15, v3
	v_add_f32_e32 v4, v17, v4
	s_waitcnt lgkmcnt(4)
	v_mfma_f32_32x32x16_bf16 v[82:97], v[244:247], v[34:37], v[82:97]
	ds_read_b64_tr_b16 v[244:245], v254 offset:13120
	ds_read_b64_tr_b16 v[246:247], v254 offset:13664
	v_add_f32_e32 v1, v18, v1
	v_add_f32_e32 v2, v19, v2
	v_add_f32_e32 v3, v20, v3
	v_add_f32_e32 v4, v21, v4
	s_waitcnt lgkmcnt(4)
	v_mfma_f32_32x32x16_bf16 v[66:81], v[38:41], v[34:37], v[66:81]
	ds_read_b64_tr_b16 v[38:39], v254 offset:13184
	ds_read_b64_tr_b16 v[40:41], v254 offset:13728
	v_cvt_pk_bf16_f32 v34, v26, v27
	v_cvt_pk_bf16_f32 v35, v28, v29
	v_cvt_pk_bf16_f32 v36, v30, v31
	v_cvt_pk_bf16_f32 v37, v32, v33
	s_nop 0
	s_waitcnt lgkmcnt(4)
	v_mfma_f32_32x32x16_bf16 v[114:129], v[250:253], v[34:37], v[114:129]
	ds_read_b64_tr_b16 v[250:251], v254 offset:13248
	ds_read_b64_tr_b16 v[252:253], v254 offset:13792
	v_add_f32_e32 v1, v22, v1
	v_add_f32_e32 v2, v23, v2
	v_add_f32_e32 v3, v24, v3
	v_add_f32_e32 v4, v25, v4
	s_waitcnt lgkmcnt(4)
	v_mfma_f32_32x32x16_bf16 v[98:113], v[244:247], v[34:37], v[98:113]
	v_add_f32_e32 v1, v26, v1
	v_add_f32_e32 v2, v27, v2
	v_add_f32_e32 v3, v28, v3
	v_add_f32_e32 v4, v29, v4
	s_waitcnt lgkmcnt(2)
	v_mfma_f32_32x32x16_bf16 v[82:97], v[38:41], v[34:37], v[82:97]
	v_add_f32_e32 v1, v30, v1
	v_add_f32_e32 v2, v31, v2
	v_add_f32_e32 v3, v32, v3
	v_add_f32_e32 v4, v33, v4
	s_waitcnt lgkmcnt(0)
	v_mfma_f32_32x32x16_bf16 v[66:81], v[250:253], v[34:37], v[66:81]
	v_add_f32_e32 v1, v1, v2
	v_add_f32_e32 v2, v3, v4
	v_add_f32_e32 v1, v1, v2
	v_add_f32_e32 v243, v243, v1
	s_branch .Lat0_done

; __device__ __forceinline__ float fexp2(float x) { return __builtin_amdgcn_exp2f(x); }
; __device__ __forceinline__ void attn_unit(const PT& p, LAS unsigned char* lds, int tid, int lane, int wave, int b, int hd, int qb, float lam) {
;     ...
;                 const float mnew = fmaxf(mrun, mx), alpha = fexp2(mrun - mnew); mrun = mnew;
;                 float rs0 = 0.f, rs1 = 0.f, rs2 = 0.f, rs3 = 0.f;
; #pragma unroll
;                 for (int kb = 0; kb < 2; ++kb)
; #pragma unroll
;                     for (int i = 0; i < 16; i += 4) { s[kb][i] = fexp2(s[kb][i] - mnew); s[kb][i + 1] = fexp2(s[kb][i + 1] - mnew); s[kb][i + 2] = fexp2(s[kb][i + 2] - mnew); s[kb][i + 3] = fexp2(s[kb][i + 3] - mnew);
;                         rs0 += s[kb][i]; rs1 += s[kb][i + 1]; rs2 += s[kb][i + 2]; rs3 += s[kb][i + 3]; }
;                 lsum = lsum * alpha + ((rs0 + rs1) + (rs2 + rs3));
.Lat0_zskip:
	s_waitcnt lgkmcnt(0)
.Lat0_done:
	s_and_b64 vcc, exec, s[78:79]
	s_cbranch_vccz .LBB0_1075

; #define LAS __attribute__((address_space(3)))
; __global__ void __launch_bounds__(512) fwd_megakernel(Params pa) {
;     extern __shared__ __attribute__((aligned(16))) unsigned char lds_raw[];
;     cg::grid_group grid = cg::this_grid();
;     LAS unsigned char* lds = (LAS unsigned char*)lds_raw;
;     if (threadIdx.x < 25) {
;         unsigned long long v = 0;
; #pragma unroll
;         for (int i = 0; i < 23; ++i) if ((int)threadIdx.x == i) v = (unsigned long long)pa.in[i];
;         if (threadIdx.x == 23) v = (unsigned long long)pa.out;
;         if (threadIdx.x == 24) v = (unsigned long long)pa.ws;
;         ((LAS unsigned long long*)(lds + PTAB_OFF))[threadIdx.x] = v;
;     }
;     if (threadIdx.x < 2) ((LAS unsigned*)(lds + XBST_OFF))[threadIdx.x] = 0u;
;     __syncthreads();
;     const XcdBarrier bar = xcd_barrier_post((unsigned*)(pa.ws + WS_BAR), (volatile LAS unsigned*)(lds + XBST_OFF));
	.amdhsa_kernel _Z14fwd_megakernel6Params
		.amdhsa_group_segment_fixed_size 0
		.amdhsa_private_segment_fixed_size 0
		.amdhsa_kernarg_size 456
		.amdhsa_user_sgpr_count 2
		.amdhsa_user_sgpr_dispatch_ptr 0
		.amdhsa_user_sgpr_queue_ptr 0
		.amdhsa_user_sgpr_kernarg_segment_ptr 1
		.amdhsa_user_sgpr_dispatch_id 0
		.amdhsa_user_sgpr_kernarg_preload_length 0
		.amdhsa_user_sgpr_kernarg_preload_offset 0
		.amdhsa_user_sgpr_private_segment_size 0
		.amdhsa_uses_dynamic_stack 0
		.amdhsa_enable_private_segment 0
		.amdhsa_system_sgpr_workgroup_id_x 1
		.amdhsa_system_sgpr_workgroup_id_y 0
		.amdhsa_system_sgpr_workgroup_id_z 0
		.amdhsa_system_sgpr_workgroup_info 0
		.amdhsa_system_vgpr_workitem_id 2
		.amdhsa_next_free_vgpr 256
		.amdhsa_next_free_sgpr 102
		.amdhsa_accum_offset 256
		.amdhsa_reserve_vcc 1
		.amdhsa_float_round_mode_32 0
		.amdhsa_float_round_mode_16_64 0
		.amdhsa_float_denorm_mode_32 3
		.amdhsa_float_denorm_mode_16_64 3
		.amdhsa_dx10_clamp 1
		.amdhsa_ieee_mode 1
		.amdhsa_fp16_overflow 0
		.amdhsa_tg_split 0
		.amdhsa_exception_fp_ieee_invalid_op 0
		.amdhsa_exception_fp_denorm_src 0
		.amdhsa_exception_fp_ieee_div_zero 0
		.amdhsa_exception_fp_ieee_overflow 0
		.amdhsa_exception_fp_ieee_underflow 0
		.amdhsa_exception_fp_ieee_inexact 0
		.amdhsa_exception_int_div_zero 0
	.end_amdhsa_kernel

; #define LAS __attribute__((address_space(3)))
; __global__ void __launch_bounds__(512) fwd_megakernel(Params pa) {
;     extern __shared__ __attribute__((aligned(16))) unsigned char lds_raw[];
;     cg::grid_group grid = cg::this_grid();
;     LAS unsigned char* lds = (LAS unsigned char*)lds_raw;
;     if (threadIdx.x < 25) {
;         unsigned long long v = 0;
; #pragma unroll
;         for (int i = 0; i < 23; ++i) if ((int)threadIdx.x == i) v = (unsigned long long)pa.in[i];
;         if (threadIdx.x == 23) v = (unsigned long long)pa.out;
;         if (threadIdx.x == 24) v = (unsigned long long)pa.ws;
;         ((LAS unsigned long long*)(lds + PTAB_OFF))[threadIdx.x] = v;
;     }
;     if (threadIdx.x < 2) ((LAS unsigned*)(lds + XBST_OFF))[threadIdx.x] = 0u;
;     __syncthreads();
;     const XcdBarrier bar = xcd_barrier_post((unsigned*)(pa.ws + WS_BAR), (volatile LAS unsigned*)(lds + XBST_OFF));
amdhsa.kernels:
  - .agpr_count:     0
    .args:
      - .offset:         0
        .size:           200
        .value_kind:     by_value
      - .offset:         200
        .size:           4
        .value_kind:     hidden_block_count_x
      - .offset:         204
        .size:           4
        .value_kind:     hidden_block_count_y
      - .offset:         208
        .size:           4
        .value_kind:     hidden_block_count_z
      - .offset:         212
        .size:           2
        .value_kind:     hidden_group_size_x
      - .offset:         214
        .size:           2
        .value_kind:     hidden_group_size_y
      - .offset:         216
        .size:           2
        .value_kind:     hidden_group_size_z
      - .offset:         218
        .size:           2
        .value_kind:     hidden_remainder_x
      - .offset:         220
        .size:           2
        .value_kind:     hidden_remainder_y
      - .offset:         222
        .size:           2
        .value_kind:     hidden_remainder_z
      - .offset:         240
        .size:           8
        .value_kind:     hidden_global_offset_x
      - .offset:         248
        .size:           8
        .value_kind:     hidden_global_offset_y
      - .offset:         256
        .size:           8
        .value_kind:     hidden_global_offset_z
      - .offset:         264
        .size:           2
        .value_kind:     hidden_grid_dims
      - .offset:         288
        .size:           8
        .value_kind:     hidden_multigrid_sync_arg
      - .offset:         320
        .size:           4
        .value_kind:     hidden_dynamic_lds_size
    .group_segment_fixed_size: 0
    .kernarg_segment_align: 8
    .kernarg_segment_size: 456
    .language:       OpenCL C
    .language_version:
      - 2
      - 0
    .max_flat_workgroup_size: 512
    .name:           _Z14fwd_megakernel6Params
    .private_segment_fixed_size: 0
    .sgpr_count:     108
    .sgpr_spill_count: 226
    .symbol:         _Z14fwd_megakernel6Params.kd
    .uniform_work_group_size: 1
    .uses_dynamic_stack: false
    .vgpr_count:     256
    .vgpr_spill_count: 0
    .wavefront_size: 64
